# v32 + two-counter syncs (P1->GEMM1, retention entry) load both counters in one round trip
# baseline (speedup 1.0000x reference)
.LBB0_196:
	global_load_dword v1, v0, s[8:9] sc1
	global_load_dword v252, v0, s[10:11] sc1
	s_mov_b64 s[12:13], -1
	s_mov_b64 s[18:19], -1
	s_waitcnt vmcnt(0)
	v_cmp_gt_u32_e32 vcc, 4, v1
	s_cbranch_vccnz .LBB0_198
	v_mov_b32_e32 v1, v252
	v_cmp_gt_u32_e64 s[18:19], s58, v1

.LBB0_301:
	global_load_dword v1, v0, s[6:7] sc1
	global_load_dword v252, v0, s[8:9] sc1
	s_mov_b64 s[18:19], -1
	s_mov_b64 s[20:21], -1
	s_waitcnt vmcnt(0)
	v_cmp_gt_u32_e32 vcc, 4, v1
	s_cbranch_vccnz .LBB0_304
	s_and_b64 vcc, exec, s[10:11]
	s_cbranch_vccz .LBB0_310
	v_mov_b32_e32 v1, v252
	v_cmp_gt_u32_e64 s[20:21], s58, v1

	.amdhsa_kernel _Z7hyb_fwd4Args
		.amdhsa_group_segment_fixed_size 0
		.amdhsa_private_segment_fixed_size 0
		.amdhsa_kernarg_size 416
		.amdhsa_user_sgpr_count 2
		.amdhsa_user_sgpr_dispatch_ptr 0
		.amdhsa_user_sgpr_queue_ptr 0
		.amdhsa_user_sgpr_kernarg_segment_ptr 1
		.amdhsa_user_sgpr_dispatch_id 0
		.amdhsa_user_sgpr_kernarg_preload_length 0
		.amdhsa_user_sgpr_kernarg_preload_offset 0
		.amdhsa_user_sgpr_private_segment_size 0
		.amdhsa_uses_dynamic_stack 0
		.amdhsa_enable_private_segment 0
		.amdhsa_system_sgpr_workgroup_id_x 1
		.amdhsa_system_sgpr_workgroup_id_y 0
		.amdhsa_system_sgpr_workgroup_id_z 0
		.amdhsa_system_sgpr_workgroup_info 0
		.amdhsa_system_vgpr_workitem_id 0
		.amdhsa_next_free_vgpr 256
		.amdhsa_next_free_sgpr 102
		.amdhsa_accum_offset 256
		.amdhsa_reserve_vcc 1
		.amdhsa_float_round_mode_32 0
		.amdhsa_float_round_mode_16_64 0
		.amdhsa_float_denorm_mode_32 3
		.amdhsa_float_denorm_mode_16_64 3
		.amdhsa_dx10_clamp 1
		.amdhsa_ieee_mode 1
		.amdhsa_fp16_overflow 0
		.amdhsa_tg_split 0
		.amdhsa_exception_fp_ieee_invalid_op 0
		.amdhsa_exception_fp_denorm_src 0
		.amdhsa_exception_fp_ieee_div_zero 0
		.amdhsa_exception_fp_ieee_overflow 0
		.amdhsa_exception_fp_ieee_underflow 0
		.amdhsa_exception_fp_ieee_inexact 0
		.amdhsa_exception_int_div_zero 0
	.end_amdhsa_kernel

amdhsa.kernels:
  - .agpr_count:     0
    .args:
      - .offset:         0
        .size:           160
        .value_kind:     by_value
      - .offset:         160
        .size:           4
        .value_kind:     hidden_block_count_x
      - .offset:         164
        .size:           4
        .value_kind:     hidden_block_count_y
      - .offset:         168
        .size:           4
        .value_kind:     hidden_block_count_z
      - .offset:         172
        .size:           2
        .value_kind:     hidden_group_size_x
      - .offset:         174
        .size:           2
        .value_kind:     hidden_group_size_y
      - .offset:         176
        .size:           2
        .value_kind:     hidden_group_size_z
      - .offset:         178
        .size:           2
        .value_kind:     hidden_remainder_x
      - .offset:         180
        .size:           2
        .value_kind:     hidden_remainder_y
      - .offset:         182
        .size:           2
        .value_kind:     hidden_remainder_z
      - .offset:         200
        .size:           8
        .value_kind:     hidden_global_offset_x
      - .offset:         208
        .size:           8
        .value_kind:     hidden_global_offset_y
      - .offset:         216
        .size:           8
        .value_kind:     hidden_global_offset_z
      - .offset:         224
        .size:           2
        .value_kind:     hidden_grid_dims
      - .offset:         280
        .size:           4
        .value_kind:     hidden_dynamic_lds_size
    .group_segment_fixed_size: 0
    .kernarg_segment_align: 8
    .kernarg_segment_size: 416
    .language:       OpenCL C
    .language_version:
      - 2
      - 0
    .max_flat_workgroup_size: 512
    .name:           _Z7hyb_fwd4Args
    .private_segment_fixed_size: 0
    .sgpr_count:     104
    .sgpr_spill_count: 45
    .symbol:         _Z7hyb_fwd4Args.kd
    .uniform_work_group_size: 1
    .uses_dynamic_stack: false
    .vgpr_count:     256
    .vgpr_spill_count: 0
    .wavefront_size: 64
